# add: middle arriver of each XCD issues a speculative early L2 writeback in the grid barrier
# speedup vs baseline: 1.0037x; 1.0037x over previous
.LBB0_406:
	s_or_b64 exec, exec, s[4:5]
	v_cvt_f32_u32_e32 v5, v3
	s_waitcnt vmcnt(0)
	v_readfirstlane_b32 s2, v4
	v_sub_u32_e32 v4, 0, v3
	v_rcp_iflag_f32_e32 v5, v5
	v_add_u32_e32 v6, s2, v0
	v_mul_f32_e32 v5, 0x4f7ffffe, v5
	v_cvt_u32_f32_e32 v5, v5
	v_mul_lo_u32 v0, v4, v5
	v_mul_hi_u32 v0, v5, v0
	v_add_u32_e32 v0, v5, v0
	v_mul_hi_u32 v0, v6, v0
	v_mul_lo_u32 v4, v0, v3
	v_sub_u32_e32 v4, v6, v4
	v_add_u32_e32 v5, 1, v0
	v_cmp_ge_u32_e32 vcc, v4, v3
	s_nop 1
	v_cndmask_b32_e32 v0, v0, v5, vcc
	v_sub_u32_e32 v5, v4, v3
	v_cndmask_b32_e32 v4, v4, v5, vcc
	v_add_u32_e32 v5, 1, v0
	v_cmp_ge_u32_e32 vcc, v4, v3
	v_add_u32_e32 v4, 1, v6
	s_nop 0
	v_cndmask_b32_e32 v0, v0, v5, vcc
	v_mul_lo_u32 v5, v3, v0
	v_add_u32_e32 v3, v5, v3
	v_cmp_ne_u32_e32 vcc, v4, v3
	s_and_saveexec_b64 s[2:3], vcc
	s_xor_b64 s[2:3], exec, s[2:3]
	s_cbranch_execz .LBB0_420
	v_sub_u32_e32 v2, v6, v5
	v_sub_u32_e32 v4, v3, v5
	v_lshrrev_b32_e32 v4, 1, v4
	v_cmp_eq_u32_e32 vcc, v2, v4
	s_cbranch_vccz .Learlywb_skip0
	buffer_wbl2 sc1
.Learlywb_skip0:
	s_movk_i32 s86, 0xd40
	s_lshl_b64 s[4:5], s[86:87], 2
	v_readlane_b32 s6, v252, 44
	v_readlane_b32 s7, v252, 45
	s_add_u32 s6, s6, s4
	s_addc_u32 s7, s7, s5
	s_waitcnt lgkmcnt(0)
	s_nop 1
	buffer_inv sc1
	global_load_dword v2, v1, s[6:7] sc1
	s_waitcnt vmcnt(0)
	v_cmp_eq_u32_e32 vcc, v2, v0
	s_and_saveexec_b64 s[4:5], vcc
	s_cbranch_execz .LBB0_419
	s_mov_b32 s21, 1
	s_mov_b64 s[8:9], 0
	s_branch .LBB0_410

.LBB0_1268:
	s_or_b64 exec, exec, s[6:7]
	v_cvt_f32_u32_e32 v5, v3
	s_waitcnt vmcnt(0)
	v_readfirstlane_b32 s4, v4
	v_sub_u32_e32 v4, 0, v3
	v_rcp_iflag_f32_e32 v5, v5
	v_add_u32_e32 v6, s4, v0
	v_mul_f32_e32 v5, 0x4f7ffffe, v5
	v_cvt_u32_f32_e32 v5, v5
	v_mul_lo_u32 v0, v4, v5
	v_mul_hi_u32 v0, v5, v0
	v_add_u32_e32 v0, v5, v0
	v_mul_hi_u32 v0, v6, v0
	v_mul_lo_u32 v4, v0, v3
	v_sub_u32_e32 v4, v6, v4
	v_add_u32_e32 v5, 1, v0
	v_cmp_ge_u32_e32 vcc, v4, v3
	s_nop 1
	v_cndmask_b32_e32 v0, v0, v5, vcc
	v_sub_u32_e32 v5, v4, v3
	v_cndmask_b32_e32 v4, v4, v5, vcc
	v_add_u32_e32 v5, 1, v0
	v_cmp_ge_u32_e32 vcc, v4, v3
	v_add_u32_e32 v4, 1, v6
	s_nop 0
	v_cndmask_b32_e32 v0, v0, v5, vcc
	v_mul_lo_u32 v5, v3, v0
	v_add_u32_e32 v3, v5, v3
	v_cmp_ne_u32_e32 vcc, v4, v3
	s_and_saveexec_b64 s[4:5], vcc
	s_xor_b64 s[4:5], exec, s[4:5]
	s_cbranch_execz .LBB0_1282
	v_sub_u32_e32 v2, v6, v5
	v_sub_u32_e32 v4, v3, v5
	v_lshrrev_b32_e32 v4, 1, v4
	v_cmp_eq_u32_e32 vcc, v2, v4
	s_cbranch_vccz .Learlywb_skip7
	buffer_wbl2 sc1
.Learlywb_skip7:
	s_movk_i32 s86, 0xd40
	s_lshl_b64 s[6:7], s[86:87], 2
	v_readlane_b32 s8, v252, 44
	v_readlane_b32 s9, v252, 45
	s_add_u32 s8, s8, s6
	s_addc_u32 s9, s9, s7
	s_waitcnt lgkmcnt(0)
	s_nop 1
	buffer_inv sc1
	global_load_dword v2, v1, s[8:9] sc1
	s_waitcnt vmcnt(0)
	v_cmp_eq_u32_e32 vcc, v2, v0
	s_and_saveexec_b64 s[6:7], vcc
	s_cbranch_execz .LBB0_1281
	s_mov_b32 s21, 1
	s_mov_b64 s[10:11], 0
	s_branch .LBB0_1272
